# v11 + merge0 / merge1: workgroups with id bit 3 set run their half tile first (same order in both merges)
# speedup vs baseline: 1.0127x; 1.0017x over previous
.LBB0_863:
	s_mov_b64 s[4:5], 0xb800000
	v_mov_b32_e32 v12, v234
	s_cmpk_lt_i32 s2, 0x180
	v_lshl_add_u64 v[186:187], v[160:161], 0, s[4:5]
	s_cselect_b64 s[6:7], -1, 0
	v_readfirstlane_b32 s4, v12
	s_cmpk_gt_i32 s2, 0x17f
	s_mul_hi_i32 s52, s2, 0x2aaaaaab
	s_cbranch_scc1 .LBB0_879
	v_lshlrev_b32_e32 v0, 4, v12
	v_add_u32_e32 v1, 0x2000, v0
	v_ashrrev_i32_e32 v2, 31, v1
	v_lshrrev_b32_e32 v2, 22, v2
	v_add_u32_e32 v2, v1, v2
	v_ashrrev_i32_e32 v10, 10, v2
	v_mul_i32_i24_e32 v2, 0x400, v10
	v_sub_u32_e32 v1, v1, v2
	v_lshrrev_b32_e32 v2, 4, v1
	v_bitop3_b32 v1, v2, v1, 32 bitop3:0x6c
	v_ashrrev_i32_e32 v2, 31, v1
	v_lshrrev_b32_e32 v2, 26, v2
	v_add_u32_e32 v2, v1, v2
	v_lshlrev_b32_e32 v3, 3, v10
	v_ashrrev_i32_e32 v11, 6, v2
	v_and_b32_e32 v3, -16, v3
	s_mov_b64 s[8:9], 0x1200000
	v_add_u32_e32 v3, v11, v3
	v_lshl_add_u64 v[128:129], v[160:161], 0, s[8:9]
	v_and_b32_e32 v4, 3, v11
	s_mov_b32 s8, 0x1fffe0
	v_lshrrev_b32_e32 v5, 2, v3
	v_lshlrev_b32_e32 v6, 1, v3
	v_and_b32_e32 v2, 0xc0, v2
	v_and_or_b32 v4, v3, s8, v4
	v_and_b32_e32 v5, 4, v5
	v_and_b32_e32 v6, 24, v6
	v_sub_u32_e32 v1, v1, v2
	v_mov_b32_e32 v2, 1
	v_or3_b32 v4, v4, v5, v6
	v_lshlrev_b32_e32 v5, 5, v10
	v_ashrrev_i16_sdwa v1, v2, sext(v1) dst_sel:DWORD dst_unused:UNUSED_PAD src0_sel:DWORD src1_sel:BYTE_0
	v_and_b32_e32 v5, 32, v5
	v_bfe_i32 v13, v1, 0, 16
	v_add_lshl_u32 v1, v5, v13, 1
	v_lshl_add_u32 v130, v4, 11, v1
	v_lshl_add_u32 v132, v3, 11, v1
	v_bfe_i32 v1, v12, 27, 1
	v_lshrrev_b32_e32 v1, 22, v1
	v_add_u32_e32 v1, v0, v1
	v_and_b32_e32 v1, 0xfffffc00, v1
	v_sub_u32_e32 v0, v0, v1
	v_lshrrev_b32_e32 v1, 4, v0
	v_ashrrev_i32_e32 v3, 31, v12
	v_bitop3_b32 v0, v1, v0, 32 bitop3:0x6c
	v_lshrrev_b32_e32 v3, 26, v3
	v_ashrrev_i32_e32 v1, 31, v0
	v_add_u32_e32 v3, v12, v3
	v_lshrrev_b32_e32 v1, 26, v1
	v_ashrrev_i32_e32 v15, 6, v3
	v_add_u32_e32 v1, v0, v1
	v_lshlrev_b32_e32 v3, 3, v15
	v_ashrrev_i32_e32 v14, 6, v1
	v_and_b32_e32 v3, -16, v3
	v_add_u32_e32 v3, v14, v3
	v_and_b32_e32 v4, 3, v14
	v_and_or_b32 v4, v3, s8, v4
	s_mov_b32 s100, s2
	s_bitcmp1_b32 s2, 3
	s_cbranch_scc0 .Lm0_y_first
	s_cmp_eq_u32 s56, 0x100
	s_cbranch_scc0 .Lm0_y_first
	s_lshr_b32 s100, s2, 1
	s_add_u32 s100, s100, 0x100
.Lm0_y_first:
	s_mul_hi_i32 s101, s100, 0x2aaaaaab
	s_lshr_b32 s8, s101, 31
	s_ashr_i32 s9, s101, 6
	s_add_i32 s8, s9, s8
	s_mul_i32 s9, s8, 0xfffffe80
	s_add_i32 s9, s9, s100
	s_ashr_i32 s10, s9, 31
	s_lshr_b32 s10, s10, 29
	s_add_i32 s10, s9, s10
	s_ashr_i32 s5, s4, 6
	s_ashr_i32 s11, s10, 3
	s_and_b32 s10, s10, -8
	s_ashr_i32 s16, s4, 8
	s_lshl_b32 s33, s5, 10
	s_sub_i32 s9, s9, s10
	s_cmp_lt_i32 s9, 0
	s_cselect_b32 s10, 49, 48
	s_mul_i32 s9, s10, s9
	s_add_i32 s9, s9, s11
	s_ashr_i32 s10, s9, 31
	s_lshr_b32 s10, s10, 27
	s_add_i32 s10, s9, s10
	s_ashr_i32 s11, s10, 5
	s_lshl_b32 s11, s11, 3
	v_and_b32_e32 v1, 0xc0, v1
	s_sub_i32 s12, 0x60, s11
	v_sub_u32_e32 v0, v0, v1
	s_min_i32 s12, s12, 8
	v_ashrrev_i16_sdwa v0, v2, sext(v0) dst_sel:DWORD dst_unused:UNUSED_PAD src0_sel:DWORD src1_sel:BYTE_0
	s_abs_i32 s13, s12
	v_bfe_i32 v16, v0, 0, 16
	v_cvt_f32_u32_e32 v0, s13
	s_sub_i32 s15, 0, s13
	s_andn2_b32 s10, s10, 31
	s_sub_i32 s9, s9, s10
	v_rcp_iflag_f32_e32 v0, v0
	s_abs_i32 s14, s9
	s_xor_b32 s10, s9, s12
	s_ashr_i32 s10, s10, 31
	v_mul_f32_e32 v0, 0x4f7ffffe, v0
	v_cvt_u32_f32_e32 v0, v0
	v_lshrrev_b32_e32 v5, 2, v3
	v_lshlrev_b32_e32 v6, 1, v3
	v_and_b32_e32 v5, 4, v5
	v_readfirstlane_b32 s17, v0
	s_mul_i32 s15, s15, s17
	s_mul_hi_u32 s15, s17, s15
	s_add_i32 s17, s17, s15
	s_mul_hi_u32 s15, s14, s17
	s_mul_i32 s17, s15, s13
	s_sub_i32 s14, s14, s17
	s_add_i32 s17, s15, 1
	s_sub_i32 s18, s14, s13
	s_cmp_ge_u32 s14, s13
	s_cselect_b32 s15, s17, s15
	s_cselect_b32 s14, s18, s14
	s_add_i32 s17, s15, 1
	s_cmp_ge_u32 s14, s13
	s_cselect_b32 s13, s17, s15
	s_xor_b32 s13, s13, s10
	s_sub_i32 s28, s13, s10
	s_mul_i32 s10, s28, s12
	s_sub_i32 s9, s9, s10
	s_add_i32 s30, s9, s11
	s_ashr_i32 s9, s8, 31
	s_ashr_i32 s31, s30, 31
	v_and_b32_e32 v6, 24, v6
	s_lshl_b64 s[10:11], s[8:9], 11
	s_lshl_b64 s[8:9], s[30:31], 19
	s_bitcmp1_b32 s2, 3
	s_cbranch_scc0 .Lm0_y_a0
	s_cmp_eq_u32 s56, 0x100
	s_cbranch_scc0 .Lm0_y_a0
	s_and_b32 s100, s2, 1
	s_lshl_b32 s100, s100, 18
	s_or_b32 s8, s8, s100
.Lm0_y_a0:
	v_or3_b32 v4, v4, v5, v6
	v_lshlrev_b32_e32 v5, 5, v15
	s_add_u32 s12, s62, s8
	v_and_b32_e32 v5, 32, v5
	s_addc_u32 s13, s63, s9
	s_ashr_i32 s29, s28, 31
	v_add_lshl_u32 v1, v5, v16, 1
	s_lshl_b64 s[8:9], s[28:29], 19
	v_lshl_add_u32 v134, v4, 11, v1
	v_lshl_add_u32 v136, v3, 11, v1
	v_lshl_add_u64 v[0:1], v[128:129], 0, s[8:9]
	v_lshl_add_u64 v[0:1], v[0:1], 0, s[10:11]
	s_add_i32 s29, s33, 0
	v_mov_b32_e32 v135, 0
	s_add_i32 m0, s29, 0x10000
	v_lshl_add_u64 v[2:3], v[0:1], 0, v[134:135]
	v_mov_b32_e32 v131, v135
	s_mov_b64 s[8:9], 0x40000
	global_load_lds_dwordx4 v[2:3], off
	v_lshl_add_u64 v[4:5], v[0:1], 0, v[130:131]
	s_add_i32 m0, s29, 0x12000
	v_lshl_add_u64 v[6:7], v[0:1], 0, s[8:9]
	global_load_lds_dwordx4 v[4:5], off
	s_add_i32 m0, s29, 0x14000
	v_lshl_add_u64 v[8:9], v[6:7], 0, v[134:135]
	global_load_lds_dwordx4 v[8:9], off
	s_add_i32 m0, s29, 0x16000
	s_add_u32 s34, s12, s10
	v_lshl_add_u64 v[6:7], v[6:7], 0, v[130:131]
	s_addc_u32 s35, s13, s11
	s_add_i32 s31, s29, 0x2000
	global_load_lds_dwordx4 v[6:7], off
	s_mov_b32 m0, s29
	s_add_u32 s10, s34, 0x40000
	global_load_lds_dwordx4 v136, s[34:35]
	s_mov_b32 m0, s31
	s_addc_u32 s11, s35, 0
	s_add_i32 s38, s29, 0x4000
	global_load_lds_dwordx4 v132, s[34:35]
	s_mov_b32 m0, s38
	s_add_i32 s39, s29, 0x6000
	global_load_lds_dwordx4 v136, s[10:11]
	s_mov_b32 m0, s39
	v_mov_b32_e32 v137, v135
	global_load_lds_dwordx4 v132, s[10:11]
	v_mov_b32_e32 v133, v135
	s_cmp_eq_u32 s16, 1
	s_mov_b32 s40, 0
	v_lshl_add_u64 v[6:7], s[34:35], 0, v[136:137]
	s_cselect_b64 s[10:11], -1, 0
	s_cmp_lg_u32 s16, 1
	v_lshl_add_u64 v[8:9], s[34:35], 0, v[132:133]
	s_cbranch_scc1 .LBB0_866
	s_barrier

.LBB0_869:
	s_add_i32 s40, s40, 1
	s_mul_i32 s4, s40, s45
	s_mul_hi_u32 s5, s40, s46
	s_add_i32 s5, s5, s4
	s_mul_i32 s4, s40, s46
	s_add_u32 s26, s4, s2
	s_addc_u32 s27, s5, s47
	s_cmp_eq_u32 s40, 1
	s_cbranch_scc0 .Lm0_enum_skip
	s_cmp_eq_u32 s46, 0x100
	s_cbranch_scc0 .Lm0_enum_skip
	s_lshr_b32 s26, s2, 1
	s_add_u32 s26, s26, 0x100
	s_mov_b32 s27, 0
	s_bitcmp1_b32 s2, 3
	s_cselect_b32 s26, s2, s26

.LBB0_871:
	s_ashr_i32 s25, s24, 31
	s_lshl_b64 s[26:27], s[24:25], 19
	s_cmp_eq_u32 s40, 1
	s_cbranch_scc0 .Lm0_a_skip
	s_cmp_eq_u32 s46, 0x100
	s_cbranch_scc0 .Lm0_a_skip
	s_bitcmp1_b32 s2, 3
	s_cbranch_scc1 .Lm0_a_skip
	s_and_b32 s98, s2, 1
	s_lshl_b32 s98, s98, 18
	s_or_b32 s26, s26, s98

.LBB0_872:
	ds_read_b128 v[164:167], v155
	ds_read_b128 v[168:171], v155 offset:1024
	ds_read_b128 v[172:175], v155 offset:2048
	ds_read_b128 v[176:179], v155 offset:3072
	ds_read_b128 v[180:183], v156
	ds_read_b128 v[188:191], v156 offset:1024
	ds_read_b128 v[192:195], v156 offset:2048
	ds_read_b128 v[196:199], v156 offset:3072
	s_add_u32 s50, s34, 0xfffc0080
	s_addc_u32 s51, s35, -1
	s_cmp_eq_u32 s23, 12
	s_cselect_b64 vcc, -1, 0
	s_and_b64 s[36:37], vcc, exec
	v_cndmask_b32_e32 v159, v151, v149, vcc
	s_cselect_b32 s37, s21, s51
	s_cselect_b32 s36, s25, s50
	v_cndmask_b32_e32 v158, v150, v148, vcc
	v_lshl_add_u64 v[232:233], s[34:35], 0, v[138:139]
	s_add_i32 m0, s29, 0xc000
	ds_read_b128 v[200:203], v157
	ds_read_b128 v[204:207], v157 offset:1024
	ds_read_b128 v[208:211], v157 offset:2048
	ds_read_b128 v[212:215], v157 offset:3072
	ds_read_b128 v[216:219], v157 offset:4096
	ds_read_b128 v[220:223], v157 offset:5120
	ds_read_b128 v[224:227], v157 offset:6144
	ds_read_b128 v[228:231], v157 offset:7168
	global_load_lds_dwordx4 v[232:233], off
	v_lshl_add_u64 v[232:233], s[34:35], 0, v[140:141]
	s_add_i32 m0, s29, 0xe000
	s_nop 0
	global_load_lds_dwordx4 v[232:233], off
	s_waitcnt vmcnt(8)
	s_waitcnt lgkmcnt(0)
	s_barrier
	s_setprio 1
	s_waitcnt lgkmcnt(0)
	v_mfma_f32_16x16x32_bf16 v[124:127], v[164:167], v[200:203], v[124:127]
	v_mfma_f32_16x16x32_bf16 v[120:123], v[172:175], v[200:203], v[120:123]
	v_mfma_f32_16x16x32_bf16 v[112:115], v[164:167], v[208:211], v[112:115]
	v_mfma_f32_16x16x32_bf16 v[104:107], v[172:175], v[208:211], v[104:107]
	v_mfma_f32_16x16x32_bf16 v[92:95], v[164:167], v[216:219], v[92:95]
	v_mfma_f32_16x16x32_bf16 v[88:91], v[172:175], v[216:219], v[88:91]
	v_mfma_f32_16x16x32_bf16 v[84:87], v[164:167], v[224:227], v[84:87]
	v_mfma_f32_16x16x32_bf16 v[80:83], v[172:175], v[224:227], v[80:83]
	v_mfma_f32_16x16x32_bf16 v[124:127], v[168:171], v[204:207], v[124:127]
	v_mfma_f32_16x16x32_bf16 v[120:123], v[176:179], v[204:207], v[120:123]
	v_mfma_f32_16x16x32_bf16 v[112:115], v[168:171], v[212:215], v[112:115]
	v_mfma_f32_16x16x32_bf16 v[104:107], v[176:179], v[212:215], v[104:107]
	v_mfma_f32_16x16x32_bf16 v[92:95], v[168:171], v[220:223], v[92:95]
	v_mfma_f32_16x16x32_bf16 v[88:91], v[176:179], v[220:223], v[88:91]
	v_mfma_f32_16x16x32_bf16 v[84:87], v[168:171], v[228:231], v[84:87]
	v_mfma_f32_16x16x32_bf16 v[80:83], v[176:179], v[228:231], v[80:83]
	s_setprio 0
	s_setprio 1
	v_mfma_f32_16x16x32_bf16 v[116:119], v[180:183], v[200:203], v[116:119]
	v_mfma_f32_16x16x32_bf16 v[108:111], v[192:195], v[200:203], v[108:111]
	v_mfma_f32_16x16x32_bf16 v[100:103], v[180:183], v[208:211], v[100:103]
	v_mfma_f32_16x16x32_bf16 v[96:99], v[192:195], v[208:211], v[96:99]
	v_mfma_f32_16x16x32_bf16 v[76:79], v[180:183], v[216:219], v[76:79]
	v_mfma_f32_16x16x32_bf16 v[72:75], v[192:195], v[216:219], v[72:75]
	v_mfma_f32_16x16x32_bf16 v[68:71], v[180:183], v[224:227], v[68:71]
	v_mfma_f32_16x16x32_bf16 v[64:67], v[192:195], v[224:227], v[64:67]
	v_mfma_f32_16x16x32_bf16 v[116:119], v[188:191], v[204:207], v[116:119]
	v_mfma_f32_16x16x32_bf16 v[108:111], v[196:199], v[204:207], v[108:111]
	v_mfma_f32_16x16x32_bf16 v[100:103], v[188:191], v[212:215], v[100:103]
	v_mfma_f32_16x16x32_bf16 v[96:99], v[196:199], v[212:215], v[96:99]
	v_mfma_f32_16x16x32_bf16 v[76:79], v[188:191], v[220:223], v[76:79]
	v_mfma_f32_16x16x32_bf16 v[72:75], v[196:199], v[220:223], v[72:75]
	v_mfma_f32_16x16x32_bf16 v[68:71], v[188:191], v[228:231], v[68:71]
	v_mfma_f32_16x16x32_bf16 v[64:67], v[196:199], v[228:231], v[64:67]
	s_setprio 0
	s_barrier
	s_add_i32 s50, s48, s33
	v_lshl_add_u64 v[232:233], v[158:159], 0, v[134:135]
	s_mov_b32 m0, s50
	ds_read_b128 v[200:203], v157 offset:16384
	ds_read_b128 v[204:207], v157 offset:17408
	ds_read_b128 v[208:211], v157 offset:18432
	ds_read_b128 v[212:215], v157 offset:19456
	ds_read_b128 v[216:219], v157 offset:20480
	ds_read_b128 v[220:223], v157 offset:21504
	ds_read_b128 v[224:227], v157 offset:22528
	ds_read_b128 v[228:231], v157 offset:23552
	global_load_lds_dwordx4 v[232:233], off
	v_lshl_add_u64 v[236:237], v[158:159], 0, v[130:131]
	s_add_i32 m0, s50, 0x2000
	v_lshl_add_u64 v[238:239], v[158:159], 0, s[8:9]
	s_add_i32 s50, s49, s33
	global_load_lds_dwordx4 v[236:237], off
	v_lshl_add_u64 v[240:241], v[238:239], 0, v[134:135]
	s_mov_b32 m0, s50
	v_lshl_add_u64 v[238:239], v[238:239], 0, v[130:131]
	global_load_lds_dwordx4 v[240:241], off
	s_add_i32 m0, s50, 0x2000
	v_lshl_add_u64 v[240:241], s[36:37], 0, v[132:133]
	global_load_lds_dwordx4 v[238:239], off
	v_lshl_add_u64 v[238:239], s[36:37], 0, v[136:137]
	s_waitcnt vmcnt(6)
	s_waitcnt lgkmcnt(0)
	s_barrier
	s_setprio 1
	s_waitcnt lgkmcnt(0)
	s_bfe_u32 s99, s2, 0x10003
	s_sub_i32 s99, 2, s99
	s_cmp_eq_u32 s40, s99
	s_cbranch_scc0 .Lm0_kfull_a
	s_cmp_eq_u32 s46, 0x100
	s_cbranch_scc1 .Lm0_kskip_a

.Lm0_kskip_a:
	s_setprio 0
	s_barrier
	s_add_i32 s50, 0, 0x18000
	s_add_i32 s51, 0, 0x1c000
	v_add_u32_e32 v176, s50, v154
	v_add_u32_e32 v196, s51, v154
	ds_read_b128 v[164:167], v176
	ds_read_b128 v[168:171], v176 offset:1024
	ds_read_b128 v[172:175], v176 offset:2048
	ds_read_b128 v[176:179], v176 offset:3072
	ds_read_b128 v[180:183], v196
	ds_read_b128 v[188:191], v196 offset:1024
	ds_read_b128 v[192:195], v196 offset:2048
	ds_read_b128 v[196:199], v196 offset:3072
	s_add_u32 s36, s36, 0x40000
	s_addc_u32 s37, s37, 0
	s_mov_b32 m0, s38
	v_lshl_add_u64 v[242:243], s[36:37], 0, v[136:137]
	ds_read_b128 v[200:203], v157 offset:32768
	ds_read_b128 v[204:207], v157 offset:33792
	ds_read_b128 v[208:211], v157 offset:34816
	ds_read_b128 v[212:215], v157 offset:35840
	ds_read_b128 v[216:219], v157 offset:36864
	ds_read_b128 v[220:223], v157 offset:37888
	ds_read_b128 v[224:227], v157 offset:38912
	ds_read_b128 v[228:231], v157 offset:39936
	s_mov_b32 m0, s29
	s_nop 0
	global_load_lds_dwordx4 v[238:239], off
	s_mov_b32 m0, s31
	s_nop 0
	global_load_lds_dwordx4 v[240:241], off
	s_mov_b32 m0, s38
	s_nop 0
	global_load_lds_dwordx4 v[242:243], off
	v_lshl_add_u64 v[242:243], s[36:37], 0, v[132:133]
	s_mov_b32 m0, s39
	s_nop 0
	global_load_lds_dwordx4 v[242:243], off
	s_waitcnt vmcnt(8)
	s_waitcnt lgkmcnt(0)
	s_barrier
	s_setprio 1
	s_waitcnt lgkmcnt(0)
	v_mfma_f32_16x16x32_bf16 v[124:127], v[164:167], v[200:203], v[124:127]
	v_mfma_f32_16x16x32_bf16 v[120:123], v[172:175], v[200:203], v[120:123]
	v_mfma_f32_16x16x32_bf16 v[112:115], v[164:167], v[208:211], v[112:115]
	v_mfma_f32_16x16x32_bf16 v[104:107], v[172:175], v[208:211], v[104:107]
	v_mfma_f32_16x16x32_bf16 v[92:95], v[164:167], v[216:219], v[92:95]
	v_mfma_f32_16x16x32_bf16 v[88:91], v[172:175], v[216:219], v[88:91]
	v_mfma_f32_16x16x32_bf16 v[84:87], v[164:167], v[224:227], v[84:87]
	v_mfma_f32_16x16x32_bf16 v[80:83], v[172:175], v[224:227], v[80:83]
	v_mfma_f32_16x16x32_bf16 v[124:127], v[168:171], v[204:207], v[124:127]
	v_mfma_f32_16x16x32_bf16 v[120:123], v[176:179], v[204:207], v[120:123]
	v_mfma_f32_16x16x32_bf16 v[112:115], v[168:171], v[212:215], v[112:115]
	v_mfma_f32_16x16x32_bf16 v[104:107], v[176:179], v[212:215], v[104:107]
	v_mfma_f32_16x16x32_bf16 v[92:95], v[168:171], v[220:223], v[92:95]
	v_mfma_f32_16x16x32_bf16 v[88:91], v[176:179], v[220:223], v[88:91]
	v_mfma_f32_16x16x32_bf16 v[84:87], v[168:171], v[228:231], v[84:87]
	v_mfma_f32_16x16x32_bf16 v[80:83], v[176:179], v[228:231], v[80:83]
	s_setprio 0
	s_setprio 1
	v_mfma_f32_16x16x32_bf16 v[116:119], v[180:183], v[200:203], v[116:119]
	v_mfma_f32_16x16x32_bf16 v[108:111], v[192:195], v[200:203], v[108:111]
	v_mfma_f32_16x16x32_bf16 v[100:103], v[180:183], v[208:211], v[100:103]
	v_mfma_f32_16x16x32_bf16 v[96:99], v[192:195], v[208:211], v[96:99]
	v_mfma_f32_16x16x32_bf16 v[76:79], v[180:183], v[216:219], v[76:79]
	v_mfma_f32_16x16x32_bf16 v[72:75], v[192:195], v[216:219], v[72:75]
	v_mfma_f32_16x16x32_bf16 v[68:71], v[180:183], v[224:227], v[68:71]
	v_mfma_f32_16x16x32_bf16 v[64:67], v[192:195], v[224:227], v[64:67]
	v_mfma_f32_16x16x32_bf16 v[116:119], v[188:191], v[204:207], v[116:119]
	v_mfma_f32_16x16x32_bf16 v[108:111], v[196:199], v[204:207], v[108:111]
	v_mfma_f32_16x16x32_bf16 v[100:103], v[188:191], v[212:215], v[100:103]
	v_mfma_f32_16x16x32_bf16 v[96:99], v[196:199], v[212:215], v[96:99]
	v_mfma_f32_16x16x32_bf16 v[76:79], v[188:191], v[220:223], v[76:79]
	v_mfma_f32_16x16x32_bf16 v[72:75], v[196:199], v[220:223], v[72:75]
	v_mfma_f32_16x16x32_bf16 v[68:71], v[188:191], v[228:231], v[68:71]
	v_mfma_f32_16x16x32_bf16 v[64:67], v[196:199], v[228:231], v[64:67]
	s_setprio 0
	s_barrier
	s_add_i32 s36, s50, s33
	v_lshl_add_u64 v[232:233], v[232:233], 0, s[12:13]
	s_mov_b32 m0, s36
	ds_read_b128 v[200:203], v157 offset:49152
	ds_read_b128 v[204:207], v157 offset:50176
	ds_read_b128 v[208:211], v157 offset:51200
	ds_read_b128 v[212:215], v157 offset:52224
	ds_read_b128 v[216:219], v157 offset:53248
	ds_read_b128 v[220:223], v157 offset:54272
	ds_read_b128 v[224:227], v157 offset:55296
	ds_read_b128 v[228:231], v157 offset:56320
	global_load_lds_dwordx4 v[232:233], off
	v_lshl_add_u64 v[232:233], v[236:237], 0, s[12:13]
	s_add_i32 m0, s36, 0x2000
	v_lshl_add_u64 v[158:159], v[158:159], 0, s[14:15]
	s_add_i32 s36, s51, s33
	global_load_lds_dwordx4 v[232:233], off
	v_lshl_add_u64 v[232:233], v[158:159], 0, v[134:135]
	s_mov_b32 m0, s36
	v_lshl_add_u64 v[158:159], v[158:159], 0, v[130:131]
	global_load_lds_dwordx4 v[232:233], off
	s_add_i32 m0, s36, 0x2000
	s_nop 0
	global_load_lds_dwordx4 v[158:159], off
	v_lshl_add_u64 v[158:159], v[238:239], 0, s[12:13]
	s_mov_b32 m0, s41
	s_nop 0
	global_load_lds_dwordx4 v[158:159], off
	v_lshl_add_u64 v[158:159], v[240:241], 0, s[12:13]
	s_mov_b32 m0, s42
	s_nop 0
	global_load_lds_dwordx4 v[158:159], off
	s_waitcnt vmcnt(8)
	s_waitcnt lgkmcnt(0)
	s_barrier
	s_setprio 1
	s_waitcnt lgkmcnt(0)
	s_bfe_u32 s99, s2, 0x10003
	s_sub_i32 s99, 2, s99
	s_cmp_eq_u32 s40, s99
	s_cbranch_scc0 .Lm0_kfull_b
	s_cmp_eq_u32 s46, 0x100
	s_cbranch_scc1 .Lm0_kskip_b

.LBB0_875:
	s_lshl_b32 s21, s30, 8
	v_mov_b32_e32 v148, v153
	v_mov_b32_e32 v149, v152
	s_add_i32 s21, s21, s43
	s_bfe_u32 s99, s2, 0x10003
	s_sub_i32 s99, 2, s99
	s_cmp_eq_u32 s40, s99
	s_cbranch_scc0 .Lm0_rb_skip
	s_cmp_eq_u32 s46, 0x100
	s_cbranch_scc0 .Lm0_rb_skip
	s_and_b32 s98, s2, 1
	s_lshl_b32 s98, s98, 7
	s_add_i32 s21, s21, s98
.Lm0_rb_skip:
	s_andn2_b64 vcc, exec, s[4:5]
	v_add_u32_e32 v150, s21, v149
	s_lshl_b32 s21, s28, 8
	s_or_b32 s21, s21, s44
	v_lshl_add_u32 v148, v148, 3, s21
	v_ashrrev_i32_e32 v151, 31, v150
	v_ashrrev_i32_e32 v149, 31, v148
	v_lshlrev_b64 v[158:159], 12, v[150:151]
	v_lshl_add_u64 v[158:159], v[162:163], 0, v[158:159]
	v_lshlrev_b64 v[148:149], 1, v[148:149]
	v_lshl_add_u64 v[158:159], v[158:159], 0, v[148:149]
	global_load_dwordx4 v[164:167], v[158:159], off
	global_load_dwordx4 v[168:171], v[158:159], off offset:256
	v_add_u32_e32 v158, 16, v150
	v_ashrrev_i32_e32 v159, 31, v158
	v_lshlrev_b64 v[172:173], 12, v[158:159]
	v_lshl_add_u64 v[172:173], v[162:163], 0, v[172:173]
	v_lshl_add_u64 v[176:177], v[172:173], 0, v[148:149]
	global_load_dwordx4 v[172:175], v[176:177], off
	s_nop 0
	global_load_dwordx4 v[176:179], v[176:177], off offset:256
	v_lshlrev_b64 v[182:183], 11, v[150:151]
	v_lshlrev_b64 v[158:159], 11, v[158:159]
	v_add_u32_e32 v180, 32, v150
	v_lshl_add_u64 v[182:183], v[186:187], 0, v[182:183]
	v_lshl_add_u64 v[158:159], v[186:187], 0, v[158:159]
	v_lshl_add_u64 v[182:183], v[182:183], 0, v[148:149]
	v_lshl_add_u64 v[158:159], v[158:159], 0, v[148:149]
	v_ashrrev_i32_e32 v181, 31, v180
	s_mov_b64 s[4:5], -1
	s_waitcnt vmcnt(0)
	v_lshlrev_b32_e32 v188, 16, v164
	v_and_b32_e32 v189, 0xffff0000, v164
	v_lshlrev_b32_e32 v164, 16, v165
	v_and_b32_e32 v165, 0xffff0000, v165
	v_lshlrev_b32_e32 v192, 16, v168
	v_and_b32_e32 v193, 0xffff0000, v168
	v_lshlrev_b32_e32 v168, 16, v169
	v_and_b32_e32 v169, 0xffff0000, v169
	v_lshlrev_b32_e32 v194, 16, v170
	v_and_b32_e32 v195, 0xffff0000, v170
	v_lshlrev_b32_e32 v170, 16, v171
	v_and_b32_e32 v171, 0xffff0000, v171
	v_lshlrev_b32_e32 v190, 16, v166
	v_and_b32_e32 v191, 0xffff0000, v166
	v_lshlrev_b32_e32 v166, 16, v167
	v_and_b32_e32 v167, 0xffff0000, v167
	v_pk_mul_f32 v[126:127], v[126:127], v[164:165]
	v_pk_mul_f32 v[118:119], v[118:119], v[168:169]
	v_pk_mul_f32 v[164:165], v[110:111], v[170:171]
	v_lshlrev_b32_e32 v168, 16, v172
	v_and_b32_e32 v169, 0xffff0000, v172
	v_lshlrev_b32_e32 v170, 16, v173
	v_and_b32_e32 v171, 0xffff0000, v173
	v_lshlrev_b32_e32 v172, 16, v174
	v_and_b32_e32 v173, 0xffff0000, v174
	v_lshlrev_b32_e32 v174, 16, v175
	v_and_b32_e32 v175, 0xffff0000, v175
	v_pk_mul_f32 v[124:125], v[124:125], v[188:189]
	v_pk_mul_f32 v[122:123], v[122:123], v[166:167]
	v_pk_mul_f32 v[120:121], v[120:121], v[190:191]
	v_lshlrev_b32_e32 v188, 16, v176
	v_and_b32_e32 v189, 0xffff0000, v176
	v_lshlrev_b32_e32 v176, 16, v177
	v_and_b32_e32 v177, 0xffff0000, v177
	v_pk_mul_f32 v[114:115], v[114:115], v[170:171]
	v_pk_mul_f32 v[112:113], v[112:113], v[168:169]
	v_pk_mul_f32 v[106:107], v[106:107], v[174:175]
	v_pk_mul_f32 v[104:105], v[104:105], v[172:173]
	v_pk_mul_f32 v[116:117], v[116:117], v[192:193]
	v_pk_mul_f32 v[166:167], v[108:109], v[194:195]
	v_lshlrev_b32_e32 v190, 16, v178
	v_and_b32_e32 v191, 0xffff0000, v178
	v_lshlrev_b32_e32 v178, 16, v179
	v_and_b32_e32 v179, 0xffff0000, v179
	v_cvt_pk_bf16_f32 v108, v124, v125
	v_cvt_pk_bf16_f32 v109, v126, v127
	v_cvt_pk_bf16_f32 v110, v120, v121
	v_cvt_pk_bf16_f32 v111, v122, v123
	v_pk_mul_f32 v[120:121], v[102:103], v[176:177]
	v_pk_mul_f32 v[122:123], v[100:101], v[188:189]
	v_cvt_pk_bf16_f32 v100, v112, v113
	v_cvt_pk_bf16_f32 v101, v114, v115
	v_cvt_pk_bf16_f32 v102, v104, v105
	v_cvt_pk_bf16_f32 v103, v106, v107
	v_cvt_pk_bf16_f32 v116, v116, v117
	v_cvt_pk_bf16_f32 v117, v118, v119
	v_cvt_pk_bf16_f32 v118, v166, v167
	v_cvt_pk_bf16_f32 v119, v164, v165
	global_store_dwordx4 v[182:183], v[108:111], off
	global_store_dwordx4 v[182:183], v[116:119], off offset:256
	global_store_dwordx4 v[158:159], v[100:103], off
	v_pk_mul_f32 v[106:107], v[98:99], v[178:179]
	v_pk_mul_f32 v[98:99], v[96:97], v[190:191]
	v_lshlrev_b64 v[100:101], 12, v[180:181]
	v_lshl_add_u64 v[100:101], v[162:163], 0, v[100:101]
	v_cvt_pk_bf16_f32 v96, v122, v123
	v_cvt_pk_bf16_f32 v97, v120, v121
	v_cvt_pk_bf16_f32 v98, v98, v99
	v_cvt_pk_bf16_f32 v99, v106, v107
	v_add_u32_e32 v112, 48, v150
	v_lshl_add_u64 v[104:105], v[100:101], 0, v[148:149]
	global_store_dwordx4 v[158:159], v[96:99], off offset:256
	v_ashrrev_i32_e32 v113, 31, v112
	global_load_dwordx4 v[100:103], v[104:105], off
	global_load_dwordx4 v[96:99], v[104:105], off offset:256
	v_lshlrev_b64 v[104:105], 12, v[112:113]
	v_lshl_add_u64 v[104:105], v[162:163], 0, v[104:105]
	v_lshl_add_u64 v[108:109], v[104:105], 0, v[148:149]
	global_load_dwordx4 v[104:107], v[108:109], off
	s_nop 0
	global_load_dwordx4 v[108:111], v[108:109], off offset:256
	v_lshlrev_b64 v[114:115], 11, v[180:181]
	v_lshlrev_b64 v[112:113], 11, v[112:113]
	v_lshl_add_u64 v[114:115], v[186:187], 0, v[114:115]
	v_lshl_add_u64 v[112:113], v[186:187], 0, v[112:113]
	v_lshl_add_u64 v[114:115], v[114:115], 0, v[148:149]
	v_lshl_add_u64 v[112:113], v[112:113], 0, v[148:149]
	s_waitcnt vmcnt(3)
	v_lshlrev_b32_e32 v116, 16, v100
	v_and_b32_e32 v117, 0xffff0000, v100
	v_lshlrev_b32_e32 v100, 16, v101
	v_and_b32_e32 v101, 0xffff0000, v101
	v_lshlrev_b32_e32 v118, 16, v102
	v_and_b32_e32 v119, 0xffff0000, v102
	v_lshlrev_b32_e32 v102, 16, v103
	v_and_b32_e32 v103, 0xffff0000, v103
	s_waitcnt vmcnt(1)
	v_lshlrev_b32_e32 v124, 16, v104
	v_and_b32_e32 v125, 0xffff0000, v104
	v_lshlrev_b32_e32 v120, 16, v96
	v_and_b32_e32 v121, 0xffff0000, v96
	v_lshlrev_b32_e32 v96, 16, v97
	v_and_b32_e32 v97, 0xffff0000, v97
	v_lshlrev_b32_e32 v122, 16, v98
	v_and_b32_e32 v123, 0xffff0000, v98
	v_lshlrev_b32_e32 v98, 16, v99
	v_and_b32_e32 v99, 0xffff0000, v99
	v_lshlrev_b32_e32 v104, 16, v105
	v_and_b32_e32 v105, 0xffff0000, v105
	v_lshlrev_b32_e32 v126, 16, v106
	v_and_b32_e32 v127, 0xffff0000, v106
	v_lshlrev_b32_e32 v106, 16, v107
	v_and_b32_e32 v107, 0xffff0000, v107
	v_pk_mul_f32 v[94:95], v[94:95], v[100:101]
	v_pk_mul_f32 v[92:93], v[92:93], v[116:117]
	v_pk_mul_f32 v[90:91], v[90:91], v[102:103]
	v_pk_mul_f32 v[88:89], v[88:89], v[118:119]
	v_pk_mul_f32 v[84:85], v[84:85], v[124:125]
	v_pk_mul_f32 v[78:79], v[78:79], v[96:97]
	v_pk_mul_f32 v[76:77], v[76:77], v[120:121]
	v_pk_mul_f32 v[96:97], v[74:75], v[98:99]
	v_pk_mul_f32 v[98:99], v[72:73], v[122:123]
	v_pk_mul_f32 v[86:87], v[86:87], v[104:105]
	v_pk_mul_f32 v[100:101], v[82:83], v[106:107]
	v_pk_mul_f32 v[82:83], v[80:81], v[126:127]
	v_cvt_pk_bf16_f32 v72, v92, v93
	v_cvt_pk_bf16_f32 v73, v94, v95
	v_cvt_pk_bf16_f32 v74, v88, v89
	v_cvt_pk_bf16_f32 v75, v90, v91
	v_cvt_pk_bf16_f32 v80, v84, v85
	v_cvt_pk_bf16_f32 v76, v76, v77
	v_cvt_pk_bf16_f32 v77, v78, v79
	v_cvt_pk_bf16_f32 v78, v98, v99
	v_cvt_pk_bf16_f32 v79, v96, v97
	v_cvt_pk_bf16_f32 v81, v86, v87
	v_cvt_pk_bf16_f32 v82, v82, v83
	v_cvt_pk_bf16_f32 v83, v100, v101
	global_store_dwordx4 v[114:115], v[72:75], off
	global_store_dwordx4 v[114:115], v[76:79], off offset:256
	global_store_dwordx4 v[112:113], v[80:83], off
	s_waitcnt vmcnt(3)
	v_lshlrev_b32_e32 v158, 16, v108
	v_and_b32_e32 v159, 0xffff0000, v108
	v_add_u32_e32 v80, 0x80, v150
	v_lshlrev_b32_e32 v108, 16, v109
	v_and_b32_e32 v109, 0xffff0000, v109
	v_lshlrev_b32_e32 v164, 16, v110
	v_and_b32_e32 v165, 0xffff0000, v110
	v_lshlrev_b32_e32 v110, 16, v111
	v_and_b32_e32 v111, 0xffff0000, v111
	v_ashrrev_i32_e32 v81, 31, v80
	v_add_u32_e32 v82, 0x90, v150
	v_pk_mul_f32 v[72:73], v[70:71], v[108:109]
	v_pk_mul_f32 v[74:75], v[68:69], v[158:159]
	v_lshlrev_b64 v[68:69], 12, v[80:81]
	v_pk_mul_f32 v[78:79], v[66:67], v[110:111]
	v_pk_mul_f32 v[66:67], v[64:65], v[164:165]
	v_ashrrev_i32_e32 v83, 31, v82
	v_lshl_add_u64 v[68:69], v[162:163], 0, v[68:69]
	v_cvt_pk_bf16_f32 v64, v74, v75
	v_cvt_pk_bf16_f32 v65, v72, v73
	v_cvt_pk_bf16_f32 v66, v66, v67
	v_cvt_pk_bf16_f32 v67, v78, v79
	v_lshlrev_b64 v[72:73], 12, v[82:83]
	v_lshl_add_u64 v[76:77], v[68:69], 0, v[148:149]
	global_store_dwordx4 v[112:113], v[64:67], off offset:256
	s_bfe_u32 s99, s2, 0x10003
	s_sub_i32 s99, 2, s99
	s_cmp_eq_u32 s40, s99
	s_cbranch_scc0 .Lm0_epi_full
	s_cmp_eq_u32 s46, 0x100
	s_cbranch_scc1 .Lm0_epi_end

.LBB0_879:
	v_mov_b32_e32 v11, v234
	v_cndmask_b32_e64 v0, 0, 1, s[6:7]
	v_cmp_ne_u32_e64 s[4:5], 1, v0
	s_andn2_b64 vcc, exec, s[6:7]
	v_readfirstlane_b32 s6, v11
	s_cbranch_vccnz .LBB0_895
	v_lshlrev_b32_e32 v0, 4, v11
	v_add_u32_e32 v1, 0x2000, v0
	v_ashrrev_i32_e32 v2, 31, v1
	v_lshrrev_b32_e32 v2, 22, v2
	v_add_u32_e32 v2, v1, v2
	v_ashrrev_i32_e32 v10, 10, v2
	v_mul_i32_i24_e32 v2, 0x400, v10
	v_sub_u32_e32 v1, v1, v2
	v_lshrrev_b32_e32 v2, 4, v1
	v_bitop3_b32 v1, v2, v1, 32 bitop3:0x6c
	v_ashrrev_i32_e32 v2, 31, v1
	v_lshrrev_b32_e32 v2, 26, v2
	v_add_u32_e32 v2, v1, v2
	v_lshlrev_b32_e32 v3, 3, v10
	v_ashrrev_i32_e32 v12, 6, v2
	v_and_b32_e32 v3, -16, v3
	s_mov_b64 s[8:9], 0x1400000
	v_add_u32_e32 v3, v12, v3
	v_lshl_add_u64 v[128:129], v[160:161], 0, s[8:9]
	v_and_b32_e32 v4, 3, v12
	s_mov_b32 s8, 0x1fffe0
	v_lshrrev_b32_e32 v5, 2, v3
	v_lshlrev_b32_e32 v6, 1, v3
	v_and_b32_e32 v2, 0xc0, v2
	v_and_or_b32 v4, v3, s8, v4
	v_and_b32_e32 v5, 4, v5
	v_and_b32_e32 v6, 24, v6
	v_sub_u32_e32 v1, v1, v2
	v_mov_b32_e32 v2, 1
	v_or3_b32 v4, v4, v5, v6
	v_lshlrev_b32_e32 v5, 5, v10
	v_ashrrev_i16_sdwa v1, v2, sext(v1) dst_sel:DWORD dst_unused:UNUSED_PAD src0_sel:DWORD src1_sel:BYTE_0
	v_and_b32_e32 v5, 32, v5
	v_bfe_i32 v13, v1, 0, 16
	v_add_lshl_u32 v1, v5, v13, 1
	v_lshl_add_u32 v130, v4, 11, v1
	v_lshl_add_u32 v132, v3, 11, v1
	v_bfe_i32 v1, v11, 27, 1
	v_lshrrev_b32_e32 v1, 22, v1
	v_add_u32_e32 v1, v0, v1
	v_and_b32_e32 v1, 0xfffffc00, v1
	v_sub_u32_e32 v0, v0, v1
	v_lshrrev_b32_e32 v1, 4, v0
	v_ashrrev_i32_e32 v3, 31, v11
	v_bitop3_b32 v0, v1, v0, 32 bitop3:0x6c
	v_lshrrev_b32_e32 v3, 26, v3
	v_ashrrev_i32_e32 v1, 31, v0
	v_add_u32_e32 v3, v11, v3
	v_lshrrev_b32_e32 v1, 26, v1
	v_ashrrev_i32_e32 v15, 6, v3
	s_ashr_i32 s7, s6, 6
	v_add_u32_e32 v1, v0, v1
	v_lshlrev_b32_e32 v3, 3, v15
	s_ashr_i32 s16, s6, 8
	s_lshl_b32 s33, s7, 10
	v_ashrrev_i32_e32 v14, 6, v1
	v_and_b32_e32 v3, -16, v3
	s_add_u32 s38, s62, 0x3000000
	v_add_u32_e32 v3, v14, v3
	v_and_b32_e32 v4, 3, v14
	s_addc_u32 s39, s63, 0
	v_and_or_b32 v4, v3, s8, v4
	s_mov_b32 s100, s2
	s_bitcmp1_b32 s2, 3
	s_cbranch_scc0 .Lm1_y_first
	s_cmp_eq_u32 s56, 0x100
	s_cbranch_scc0 .Lm1_y_first
	s_lshr_b32 s100, s2, 1
	s_add_u32 s100, s100, 0x100
.Lm1_y_first:
	s_mul_hi_i32 s101, s100, 0x2aaaaaab
	s_lshr_b32 s8, s101, 31
	s_ashr_i32 s9, s101, 6
	s_add_i32 s8, s9, s8
	s_mul_i32 s9, s8, 0xfffffe80
	s_add_i32 s9, s9, s100
	s_ashr_i32 s10, s9, 31
	s_lshr_b32 s10, s10, 29
	s_add_i32 s10, s9, s10
	s_ashr_i32 s11, s10, 3
	s_and_b32 s10, s10, -8
	s_sub_i32 s9, s9, s10
	s_cmp_lt_i32 s9, 0
	s_cselect_b32 s10, 49, 48
	s_mul_i32 s9, s10, s9
	s_add_i32 s9, s9, s11
	s_ashr_i32 s10, s9, 31
	s_lshr_b32 s10, s10, 27
	s_add_i32 s10, s9, s10
	s_ashr_i32 s11, s10, 5
	s_lshl_b32 s11, s11, 3
	v_and_b32_e32 v1, 0xc0, v1
	s_sub_i32 s12, 0x60, s11
	v_sub_u32_e32 v0, v0, v1
	s_min_i32 s12, s12, 8
	v_ashrrev_i16_sdwa v0, v2, sext(v0) dst_sel:DWORD dst_unused:UNUSED_PAD src0_sel:DWORD src1_sel:BYTE_0
	s_abs_i32 s13, s12
	v_bfe_i32 v16, v0, 0, 16
	v_cvt_f32_u32_e32 v0, s13
	s_sub_i32 s15, 0, s13
	s_andn2_b32 s10, s10, 31
	s_sub_i32 s9, s9, s10
	v_rcp_iflag_f32_e32 v0, v0
	s_abs_i32 s14, s9
	s_xor_b32 s10, s9, s12
	s_ashr_i32 s10, s10, 31
	v_mul_f32_e32 v0, 0x4f7ffffe, v0
	v_cvt_u32_f32_e32 v0, v0
	v_lshrrev_b32_e32 v5, 2, v3
	v_lshlrev_b32_e32 v6, 1, v3
	v_and_b32_e32 v5, 4, v5
	v_readfirstlane_b32 s17, v0
	s_mul_i32 s15, s15, s17
	s_mul_hi_u32 s15, s17, s15
	s_add_i32 s17, s17, s15
	s_mul_hi_u32 s15, s14, s17
	s_mul_i32 s17, s15, s13
	s_sub_i32 s14, s14, s17
	s_add_i32 s17, s15, 1
	s_sub_i32 s18, s14, s13
	s_cmp_ge_u32 s14, s13
	s_cselect_b32 s15, s17, s15
	s_cselect_b32 s14, s18, s14
	s_add_i32 s17, s15, 1
	s_cmp_ge_u32 s14, s13
	s_cselect_b32 s13, s17, s15
	s_xor_b32 s13, s13, s10
	s_sub_i32 s28, s13, s10
	s_mul_i32 s10, s28, s12
	s_sub_i32 s9, s9, s10
	s_add_i32 s30, s9, s11
	s_ashr_i32 s9, s8, 31
	s_ashr_i32 s31, s30, 31
	v_and_b32_e32 v6, 24, v6
	s_lshl_b64 s[10:11], s[8:9], 11
	s_lshl_b64 s[8:9], s[30:31], 19
	s_bitcmp1_b32 s2, 3
	s_cbranch_scc0 .Lm1_y_a0
	s_cmp_eq_u32 s56, 0x100
	s_cbranch_scc0 .Lm1_y_a0
	s_and_b32 s100, s2, 1
	s_lshl_b32 s100, s100, 18
	s_or_b32 s8, s8, s100
.Lm1_y_a0:
	v_or3_b32 v4, v4, v5, v6
	v_lshlrev_b32_e32 v5, 5, v15
	s_add_u32 s12, s38, s8
	v_and_b32_e32 v5, 32, v5
	s_addc_u32 s13, s39, s9
	s_ashr_i32 s29, s28, 31
	v_add_lshl_u32 v1, v5, v16, 1
	s_lshl_b64 s[8:9], s[28:29], 19
	v_lshl_add_u32 v134, v4, 11, v1
	v_lshl_add_u32 v136, v3, 11, v1
	v_lshl_add_u64 v[0:1], v[128:129], 0, s[8:9]
	v_lshl_add_u64 v[0:1], v[0:1], 0, s[10:11]
	s_add_i32 s29, s33, 0
	v_mov_b32_e32 v135, 0
	s_add_i32 m0, s29, 0x10000
	v_lshl_add_u64 v[2:3], v[0:1], 0, v[134:135]
	v_mov_b32_e32 v131, v135
	s_mov_b64 s[8:9], 0x40000
	global_load_lds_dwordx4 v[2:3], off
	v_lshl_add_u64 v[4:5], v[0:1], 0, v[130:131]
	s_add_i32 m0, s29, 0x12000
	v_lshl_add_u64 v[6:7], v[0:1], 0, s[8:9]
	global_load_lds_dwordx4 v[4:5], off
	s_add_i32 m0, s29, 0x14000
	v_lshl_add_u64 v[8:9], v[6:7], 0, v[134:135]
	global_load_lds_dwordx4 v[8:9], off
	s_add_i32 m0, s29, 0x16000
	s_add_u32 s34, s12, s10
	v_lshl_add_u64 v[6:7], v[6:7], 0, v[130:131]
	s_addc_u32 s35, s13, s11
	s_add_i32 s31, s29, 0x2000
	global_load_lds_dwordx4 v[6:7], off
	s_mov_b32 m0, s29
	s_add_u32 s10, s34, 0x40000
	global_load_lds_dwordx4 v136, s[34:35]
	s_mov_b32 m0, s31
	s_addc_u32 s11, s35, 0
	s_add_i32 s40, s29, 0x4000
	global_load_lds_dwordx4 v132, s[34:35]
	s_mov_b32 m0, s40
	s_add_i32 s41, s29, 0x6000
	global_load_lds_dwordx4 v136, s[10:11]
	s_mov_b32 m0, s41
	v_mov_b32_e32 v137, v135
	global_load_lds_dwordx4 v132, s[10:11]
	v_mov_b32_e32 v133, v135
	s_cmp_eq_u32 s16, 1
	s_mov_b32 s42, 0
	v_lshl_add_u64 v[6:7], s[34:35], 0, v[136:137]
	s_cselect_b64 s[10:11], -1, 0
	s_cmp_lg_u32 s16, 1
	v_lshl_add_u64 v[8:9], s[34:35], 0, v[132:133]
	s_cbranch_scc1 .LBB0_882
	s_barrier

.LBB0_885:
	s_add_i32 s42, s42, 1
	s_mul_i32 s6, s42, s47
	s_mul_hi_u32 s7, s42, s48
	s_add_i32 s7, s7, s6
	s_mul_i32 s6, s42, s48
	s_add_u32 s26, s6, s2
	s_addc_u32 s27, s7, s49
	s_cmp_eq_u32 s42, 1
	s_cbranch_scc0 .Lm1_enum_skip
	s_cmp_eq_u32 s48, 0x100
	s_cbranch_scc0 .Lm1_enum_skip
	s_lshr_b32 s26, s2, 1
	s_add_u32 s26, s26, 0x100
	s_mov_b32 s27, 0
	s_bitcmp1_b32 s2, 3
	s_cselect_b32 s26, s2, s26

.LBB0_887:
	s_ashr_i32 s25, s24, 31
	s_lshl_b64 s[26:27], s[24:25], 19
	s_cmp_eq_u32 s42, 1
	s_cbranch_scc0 .Lm1_a_skip
	s_cmp_eq_u32 s48, 0x100
	s_cbranch_scc0 .Lm1_a_skip
	s_bitcmp1_b32 s2, 3
	s_cbranch_scc1 .Lm1_a_skip
	s_and_b32 s98, s2, 1
	s_lshl_b32 s98, s98, 18
	s_or_b32 s26, s26, s98

.LBB0_888:
	ds_read_b128 v[164:167], v155
	ds_read_b128 v[168:171], v155 offset:1024
	ds_read_b128 v[172:175], v155 offset:2048
	ds_read_b128 v[176:179], v155 offset:3072
	ds_read_b128 v[180:183], v156
	ds_read_b128 v[188:191], v156 offset:1024
	ds_read_b128 v[192:195], v156 offset:2048
	ds_read_b128 v[196:199], v156 offset:3072
	s_add_u32 s53, s34, 0xfffc0080
	s_addc_u32 s54, s35, -1
	s_cmp_eq_u32 s23, 12
	s_cselect_b64 vcc, -1, 0
	s_and_b64 s[36:37], vcc, exec
	v_cndmask_b32_e32 v159, v151, v149, vcc
	s_cselect_b32 s37, s21, s54
	s_cselect_b32 s36, s25, s53
	v_cndmask_b32_e32 v158, v150, v148, vcc
	v_lshl_add_u64 v[232:233], s[34:35], 0, v[138:139]
	s_add_i32 m0, s29, 0xc000
	ds_read_b128 v[200:203], v157
	ds_read_b128 v[204:207], v157 offset:1024
	ds_read_b128 v[208:211], v157 offset:2048
	ds_read_b128 v[212:215], v157 offset:3072
	ds_read_b128 v[216:219], v157 offset:4096
	ds_read_b128 v[220:223], v157 offset:5120
	ds_read_b128 v[224:227], v157 offset:6144
	ds_read_b128 v[228:231], v157 offset:7168
	global_load_lds_dwordx4 v[232:233], off
	v_lshl_add_u64 v[232:233], s[34:35], 0, v[140:141]
	s_add_i32 m0, s29, 0xe000
	s_nop 0
	global_load_lds_dwordx4 v[232:233], off
	s_waitcnt vmcnt(8)
	s_waitcnt lgkmcnt(0)
	s_barrier
	s_setprio 1
	s_waitcnt lgkmcnt(0)
	v_mfma_f32_16x16x32_bf16 v[124:127], v[164:167], v[200:203], v[124:127]
	v_mfma_f32_16x16x32_bf16 v[120:123], v[172:175], v[200:203], v[120:123]
	v_mfma_f32_16x16x32_bf16 v[108:111], v[164:167], v[208:211], v[108:111]
	v_mfma_f32_16x16x32_bf16 v[104:107], v[172:175], v[208:211], v[104:107]
	v_mfma_f32_16x16x32_bf16 v[92:95], v[164:167], v[216:219], v[92:95]
	v_mfma_f32_16x16x32_bf16 v[88:91], v[172:175], v[216:219], v[88:91]
	v_mfma_f32_16x16x32_bf16 v[76:79], v[164:167], v[224:227], v[76:79]
	v_mfma_f32_16x16x32_bf16 v[72:75], v[172:175], v[224:227], v[72:75]
	v_mfma_f32_16x16x32_bf16 v[124:127], v[168:171], v[204:207], v[124:127]
	v_mfma_f32_16x16x32_bf16 v[120:123], v[176:179], v[204:207], v[120:123]
	v_mfma_f32_16x16x32_bf16 v[108:111], v[168:171], v[212:215], v[108:111]
	v_mfma_f32_16x16x32_bf16 v[104:107], v[176:179], v[212:215], v[104:107]
	v_mfma_f32_16x16x32_bf16 v[92:95], v[168:171], v[220:223], v[92:95]
	v_mfma_f32_16x16x32_bf16 v[88:91], v[176:179], v[220:223], v[88:91]
	v_mfma_f32_16x16x32_bf16 v[76:79], v[168:171], v[228:231], v[76:79]
	v_mfma_f32_16x16x32_bf16 v[72:75], v[176:179], v[228:231], v[72:75]
	s_setprio 0
	s_setprio 1
	v_mfma_f32_16x16x32_bf16 v[116:119], v[180:183], v[200:203], v[116:119]
	v_mfma_f32_16x16x32_bf16 v[112:115], v[192:195], v[200:203], v[112:115]
	v_mfma_f32_16x16x32_bf16 v[100:103], v[180:183], v[208:211], v[100:103]
	v_mfma_f32_16x16x32_bf16 v[96:99], v[192:195], v[208:211], v[96:99]
	v_mfma_f32_16x16x32_bf16 v[84:87], v[180:183], v[216:219], v[84:87]
	v_mfma_f32_16x16x32_bf16 v[80:83], v[192:195], v[216:219], v[80:83]
	v_mfma_f32_16x16x32_bf16 v[68:71], v[180:183], v[224:227], v[68:71]
	v_mfma_f32_16x16x32_bf16 v[64:67], v[192:195], v[224:227], v[64:67]
	v_mfma_f32_16x16x32_bf16 v[116:119], v[188:191], v[204:207], v[116:119]
	v_mfma_f32_16x16x32_bf16 v[112:115], v[196:199], v[204:207], v[112:115]
	v_mfma_f32_16x16x32_bf16 v[100:103], v[188:191], v[212:215], v[100:103]
	v_mfma_f32_16x16x32_bf16 v[96:99], v[196:199], v[212:215], v[96:99]
	v_mfma_f32_16x16x32_bf16 v[84:87], v[188:191], v[220:223], v[84:87]
	v_mfma_f32_16x16x32_bf16 v[80:83], v[196:199], v[220:223], v[80:83]
	v_mfma_f32_16x16x32_bf16 v[68:71], v[188:191], v[228:231], v[68:71]
	v_mfma_f32_16x16x32_bf16 v[64:67], v[196:199], v[228:231], v[64:67]
	s_setprio 0
	s_barrier
	s_add_i32 s53, s50, s33
	v_lshl_add_u64 v[232:233], v[158:159], 0, v[134:135]
	s_mov_b32 m0, s53
	ds_read_b128 v[200:203], v157 offset:16384
	ds_read_b128 v[204:207], v157 offset:17408
	ds_read_b128 v[208:211], v157 offset:18432
	ds_read_b128 v[212:215], v157 offset:19456
	ds_read_b128 v[216:219], v157 offset:20480
	ds_read_b128 v[220:223], v157 offset:21504
	ds_read_b128 v[224:227], v157 offset:22528
	ds_read_b128 v[228:231], v157 offset:23552
	global_load_lds_dwordx4 v[232:233], off
	v_lshl_add_u64 v[236:237], v[158:159], 0, v[130:131]
	s_add_i32 m0, s53, 0x2000
	v_lshl_add_u64 v[238:239], v[158:159], 0, s[8:9]
	s_add_i32 s53, s51, s33
	global_load_lds_dwordx4 v[236:237], off
	v_lshl_add_u64 v[240:241], v[238:239], 0, v[134:135]
	s_mov_b32 m0, s53
	v_lshl_add_u64 v[238:239], v[238:239], 0, v[130:131]
	global_load_lds_dwordx4 v[240:241], off
	s_add_i32 m0, s53, 0x2000
	v_lshl_add_u64 v[240:241], s[36:37], 0, v[132:133]
	global_load_lds_dwordx4 v[238:239], off
	v_lshl_add_u64 v[238:239], s[36:37], 0, v[136:137]
	s_waitcnt vmcnt(6)
	s_waitcnt lgkmcnt(0)
	s_barrier
	s_setprio 1
	s_waitcnt lgkmcnt(0)
	s_bfe_u32 s99, s2, 0x10003
	s_sub_i32 s99, 2, s99
	s_cmp_eq_u32 s42, s99
	s_cbranch_scc0 .Lm1_kfull_a
	s_cmp_eq_u32 s48, 0x100
	s_cbranch_scc1 .Lm1_kskip_a

.Lm1_kskip_a:
	s_setprio 0
	s_barrier
	s_add_i32 s53, 0, 0x18000
	s_add_i32 s54, 0, 0x1c000
	v_add_u32_e32 v176, s53, v154
	v_add_u32_e32 v196, s54, v154
	ds_read_b128 v[164:167], v176
	ds_read_b128 v[168:171], v176 offset:1024
	ds_read_b128 v[172:175], v176 offset:2048
	ds_read_b128 v[176:179], v176 offset:3072
	ds_read_b128 v[180:183], v196
	ds_read_b128 v[188:191], v196 offset:1024
	ds_read_b128 v[192:195], v196 offset:2048
	ds_read_b128 v[196:199], v196 offset:3072
	s_add_u32 s36, s36, 0x40000
	s_addc_u32 s37, s37, 0
	s_mov_b32 m0, s40
	v_lshl_add_u64 v[242:243], s[36:37], 0, v[136:137]
	ds_read_b128 v[200:203], v157 offset:32768
	ds_read_b128 v[204:207], v157 offset:33792
	ds_read_b128 v[208:211], v157 offset:34816
	ds_read_b128 v[212:215], v157 offset:35840
	ds_read_b128 v[216:219], v157 offset:36864
	ds_read_b128 v[220:223], v157 offset:37888
	ds_read_b128 v[224:227], v157 offset:38912
	ds_read_b128 v[228:231], v157 offset:39936
	s_mov_b32 m0, s29
	s_nop 0
	global_load_lds_dwordx4 v[238:239], off
	s_mov_b32 m0, s31
	s_nop 0
	global_load_lds_dwordx4 v[240:241], off
	s_mov_b32 m0, s40
	s_nop 0
	global_load_lds_dwordx4 v[242:243], off
	v_lshl_add_u64 v[242:243], s[36:37], 0, v[132:133]
	s_mov_b32 m0, s41
	s_nop 0
	global_load_lds_dwordx4 v[242:243], off
	s_waitcnt vmcnt(8)
	s_waitcnt lgkmcnt(0)
	s_barrier
	s_setprio 1
	s_waitcnt lgkmcnt(0)
	v_mfma_f32_16x16x32_bf16 v[124:127], v[164:167], v[200:203], v[124:127]
	v_mfma_f32_16x16x32_bf16 v[120:123], v[172:175], v[200:203], v[120:123]
	v_mfma_f32_16x16x32_bf16 v[108:111], v[164:167], v[208:211], v[108:111]
	v_mfma_f32_16x16x32_bf16 v[104:107], v[172:175], v[208:211], v[104:107]
	v_mfma_f32_16x16x32_bf16 v[92:95], v[164:167], v[216:219], v[92:95]
	v_mfma_f32_16x16x32_bf16 v[88:91], v[172:175], v[216:219], v[88:91]
	v_mfma_f32_16x16x32_bf16 v[76:79], v[164:167], v[224:227], v[76:79]
	v_mfma_f32_16x16x32_bf16 v[72:75], v[172:175], v[224:227], v[72:75]
	v_mfma_f32_16x16x32_bf16 v[124:127], v[168:171], v[204:207], v[124:127]
	v_mfma_f32_16x16x32_bf16 v[120:123], v[176:179], v[204:207], v[120:123]
	v_mfma_f32_16x16x32_bf16 v[108:111], v[168:171], v[212:215], v[108:111]
	v_mfma_f32_16x16x32_bf16 v[104:107], v[176:179], v[212:215], v[104:107]
	v_mfma_f32_16x16x32_bf16 v[92:95], v[168:171], v[220:223], v[92:95]
	v_mfma_f32_16x16x32_bf16 v[88:91], v[176:179], v[220:223], v[88:91]
	v_mfma_f32_16x16x32_bf16 v[76:79], v[168:171], v[228:231], v[76:79]
	v_mfma_f32_16x16x32_bf16 v[72:75], v[176:179], v[228:231], v[72:75]
	s_setprio 0
	s_setprio 1
	v_mfma_f32_16x16x32_bf16 v[116:119], v[180:183], v[200:203], v[116:119]
	v_mfma_f32_16x16x32_bf16 v[112:115], v[192:195], v[200:203], v[112:115]
	v_mfma_f32_16x16x32_bf16 v[100:103], v[180:183], v[208:211], v[100:103]
	v_mfma_f32_16x16x32_bf16 v[96:99], v[192:195], v[208:211], v[96:99]
	v_mfma_f32_16x16x32_bf16 v[84:87], v[180:183], v[216:219], v[84:87]
	v_mfma_f32_16x16x32_bf16 v[80:83], v[192:195], v[216:219], v[80:83]
	v_mfma_f32_16x16x32_bf16 v[68:71], v[180:183], v[224:227], v[68:71]
	v_mfma_f32_16x16x32_bf16 v[64:67], v[192:195], v[224:227], v[64:67]
	v_mfma_f32_16x16x32_bf16 v[116:119], v[188:191], v[204:207], v[116:119]
	v_mfma_f32_16x16x32_bf16 v[112:115], v[196:199], v[204:207], v[112:115]
	v_mfma_f32_16x16x32_bf16 v[100:103], v[188:191], v[212:215], v[100:103]
	v_mfma_f32_16x16x32_bf16 v[96:99], v[196:199], v[212:215], v[96:99]
	v_mfma_f32_16x16x32_bf16 v[84:87], v[188:191], v[220:223], v[84:87]
	v_mfma_f32_16x16x32_bf16 v[80:83], v[196:199], v[220:223], v[80:83]
	v_mfma_f32_16x16x32_bf16 v[68:71], v[188:191], v[228:231], v[68:71]
	v_mfma_f32_16x16x32_bf16 v[64:67], v[196:199], v[228:231], v[64:67]
	s_setprio 0
	s_barrier
	s_add_i32 s36, s53, s33
	v_lshl_add_u64 v[232:233], v[232:233], 0, s[12:13]
	s_mov_b32 m0, s36
	ds_read_b128 v[200:203], v157 offset:49152
	ds_read_b128 v[204:207], v157 offset:50176
	ds_read_b128 v[208:211], v157 offset:51200
	ds_read_b128 v[212:215], v157 offset:52224
	ds_read_b128 v[216:219], v157 offset:53248
	ds_read_b128 v[220:223], v157 offset:54272
	ds_read_b128 v[224:227], v157 offset:55296
	ds_read_b128 v[228:231], v157 offset:56320
	global_load_lds_dwordx4 v[232:233], off
	v_lshl_add_u64 v[232:233], v[236:237], 0, s[12:13]
	s_add_i32 m0, s36, 0x2000
	v_lshl_add_u64 v[158:159], v[158:159], 0, s[14:15]
	s_add_i32 s36, s54, s33
	global_load_lds_dwordx4 v[232:233], off
	v_lshl_add_u64 v[232:233], v[158:159], 0, v[134:135]
	s_mov_b32 m0, s36
	v_lshl_add_u64 v[158:159], v[158:159], 0, v[130:131]
	global_load_lds_dwordx4 v[232:233], off
	s_add_i32 m0, s36, 0x2000
	s_nop 0
	global_load_lds_dwordx4 v[158:159], off
	v_lshl_add_u64 v[158:159], v[238:239], 0, s[12:13]
	s_mov_b32 m0, s43
	s_nop 0
	global_load_lds_dwordx4 v[158:159], off
	v_lshl_add_u64 v[158:159], v[240:241], 0, s[12:13]
	s_mov_b32 m0, s44
	s_nop 0
	global_load_lds_dwordx4 v[158:159], off
	s_waitcnt vmcnt(8)
	s_waitcnt lgkmcnt(0)
	s_barrier
	s_setprio 1
	s_waitcnt lgkmcnt(0)
	s_bfe_u32 s99, s2, 0x10003
	s_sub_i32 s99, 2, s99
	s_cmp_eq_u32 s42, s99
	s_cbranch_scc0 .Lm1_kfull_b
	s_cmp_eq_u32 s48, 0x100
	s_cbranch_scc1 .Lm1_kskip_b

.LBB0_891:
	v_mov_b32_e32 v148, v152
	v_mov_b32_e32 v149, v153
	s_lshl_b32 s21, s30, 8
	s_add_i32 s21, s21, s45
	s_bfe_u32 s99, s2, 0x10003
	s_sub_i32 s99, 2, s99
	s_cmp_eq_u32 s42, s99
	s_cbranch_scc0 .Lm1_rb_skip
	s_cmp_eq_u32 s48, 0x100
	s_cbranch_scc0 .Lm1_rb_skip
	s_and_b32 s98, s2, 1
	s_lshl_b32 s98, s98, 7
	s_add_i32 s21, s21, s98
.Lm1_rb_skip:
	v_add_u32_e32 v148, s21, v148
	s_lshl_b32 s21, s28, 8
	s_or_b32 s21, s21, s46
	v_lshl_add_u32 v150, v149, 3, s21
	v_ashrrev_i32_e32 v149, 31, v148
	v_ashrrev_i32_e32 v151, 31, v150
	v_lshlrev_b64 v[158:159], 12, v[148:149]
	v_lshlrev_b64 v[168:169], 11, v[148:149]
	v_lshl_add_u64 v[158:159], v[162:163], 0, v[158:159]
	v_lshlrev_b64 v[150:151], 1, v[150:151]
	v_lshl_add_u64 v[168:169], v[186:187], 0, v[168:169]
	v_lshl_add_u64 v[158:159], v[158:159], 0, v[150:151]
	v_lshl_add_u64 v[200:201], v[168:169], 0, v[150:151]
	global_load_dwordx4 v[164:167], v[158:159], off offset:2048
	global_load_dwordx4 v[168:171], v[200:201], off
	global_load_dwordx4 v[172:175], v[158:159], off offset:2304
	global_load_dwordx4 v[176:179], v[200:201], off offset:256
	v_add_u32_e32 v158, 16, v148
	v_ashrrev_i32_e32 v159, 31, v158
	v_lshlrev_b64 v[180:181], 12, v[158:159]
	v_lshl_add_u64 v[180:181], v[162:163], 0, v[180:181]
	v_lshl_add_u64 v[192:193], v[180:181], 0, v[150:151]
	v_lshlrev_b64 v[158:159], 11, v[158:159]
	global_load_dwordx4 v[180:183], v[192:193], off offset:2048
	v_lshl_add_u64 v[158:159], v[186:187], 0, v[158:159]
	v_lshl_add_u64 v[158:159], v[158:159], 0, v[150:151]
	global_load_dwordx4 v[188:191], v[158:159], off
	s_nop 0
	global_load_dwordx4 v[192:195], v[192:193], off offset:2304
	s_nop 0
	global_load_dwordx4 v[196:199], v[158:159], off offset:256
	s_andn2_b64 vcc, exec, s[6:7]
	s_mov_b64 s[6:7], -1
	s_waitcnt vmcnt(0)
	v_lshlrev_b32_e32 v206, 16, v168
	v_lshlrev_b32_e32 v202, 16, v164
	v_and_b32_e32 v203, 0xffff0000, v164
	v_lshlrev_b32_e32 v164, 16, v165
	v_and_b32_e32 v165, 0xffff0000, v165
	v_lshlrev_b32_e32 v204, 16, v166
	v_and_b32_e32 v205, 0xffff0000, v166
	v_lshlrev_b32_e32 v166, 16, v167
	v_and_b32_e32 v167, 0xffff0000, v167
	v_and_b32_e32 v207, 0xffff0000, v168
	v_lshlrev_b32_e32 v168, 16, v169
	v_and_b32_e32 v169, 0xffff0000, v169
	v_lshlrev_b32_e32 v208, 16, v170
	v_and_b32_e32 v209, 0xffff0000, v170
	v_lshlrev_b32_e32 v170, 16, v171
	v_and_b32_e32 v171, 0xffff0000, v171
	v_lshlrev_b32_e32 v210, 16, v172
	v_and_b32_e32 v211, 0xffff0000, v172
	v_lshlrev_b32_e32 v172, 16, v173
	v_and_b32_e32 v173, 0xffff0000, v173
	v_lshlrev_b32_e32 v212, 16, v174
	v_and_b32_e32 v213, 0xffff0000, v174
	v_lshlrev_b32_e32 v174, 16, v175
	v_and_b32_e32 v175, 0xffff0000, v175
	v_lshlrev_b32_e32 v214, 16, v176
	v_and_b32_e32 v215, 0xffff0000, v176
	v_lshlrev_b32_e32 v176, 16, v177
	v_and_b32_e32 v177, 0xffff0000, v177
	v_lshlrev_b32_e32 v216, 16, v178
	v_and_b32_e32 v217, 0xffff0000, v178
	v_lshlrev_b32_e32 v178, 16, v179
	v_and_b32_e32 v179, 0xffff0000, v179
	v_pk_fma_f32 v[126:127], v[126:127], v[164:165], v[168:169]
	v_pk_fma_f32 v[124:125], v[124:125], v[202:203], v[206:207]
	v_pk_fma_f32 v[122:123], v[122:123], v[166:167], v[170:171]
	v_pk_fma_f32 v[120:121], v[120:121], v[204:205], v[208:209]
	v_pk_fma_f32 v[118:119], v[118:119], v[172:173], v[176:177]
	v_pk_fma_f32 v[116:117], v[116:117], v[210:211], v[214:215]
	v_pk_fma_f32 v[164:165], v[114:115], v[174:175], v[178:179]
	v_pk_fma_f32 v[166:167], v[112:113], v[212:213], v[216:217]
	v_cvt_pk_bf16_f32 v112, v124, v125
	v_cvt_pk_bf16_f32 v113, v126, v127
	v_cvt_pk_bf16_f32 v114, v120, v121
	v_cvt_pk_bf16_f32 v115, v122, v123
	v_lshlrev_b32_e32 v168, 16, v180
	v_and_b32_e32 v169, 0xffff0000, v180
	v_cvt_pk_bf16_f32 v116, v116, v117
	v_cvt_pk_bf16_f32 v117, v118, v119
	v_cvt_pk_bf16_f32 v118, v166, v167
	v_cvt_pk_bf16_f32 v119, v164, v165
	global_store_dwordx4 v[200:201], v[112:115], off
	global_store_dwordx4 v[200:201], v[116:119], off offset:256
	v_lshlrev_b32_e32 v170, 16, v181
	v_lshlrev_b32_e32 v112, 16, v188
	v_and_b32_e32 v113, 0xffff0000, v188
	v_and_b32_e32 v171, 0xffff0000, v181
	v_lshlrev_b32_e32 v172, 16, v182
	v_and_b32_e32 v173, 0xffff0000, v182
	v_lshlrev_b32_e32 v174, 16, v183
	v_and_b32_e32 v175, 0xffff0000, v183
	v_lshlrev_b32_e32 v114, 16, v189
	v_and_b32_e32 v115, 0xffff0000, v189
	v_lshlrev_b32_e32 v116, 16, v190
	v_and_b32_e32 v117, 0xffff0000, v190
	v_lshlrev_b32_e32 v118, 16, v191
	v_and_b32_e32 v119, 0xffff0000, v191
	v_pk_fma_f32 v[108:109], v[108:109], v[168:169], v[112:113]
	v_pk_fma_f32 v[110:111], v[110:111], v[170:171], v[114:115]
	v_pk_fma_f32 v[112:113], v[106:107], v[174:175], v[118:119]
	v_pk_fma_f32 v[106:107], v[104:105], v[172:173], v[116:117]
	v_cvt_pk_bf16_f32 v104, v108, v109
	v_add_u32_e32 v108, 32, v148
	v_cvt_pk_bf16_f32 v105, v110, v111
	v_cvt_pk_bf16_f32 v106, v106, v107
	v_cvt_pk_bf16_f32 v107, v112, v113
	v_ashrrev_i32_e32 v109, 31, v108
	global_store_dwordx4 v[158:159], v[104:107], off
	v_lshlrev_b32_e32 v112, 16, v192
	v_and_b32_e32 v113, 0xffff0000, v192
	v_lshlrev_b64 v[104:105], 11, v[108:109]
	v_lshlrev_b64 v[108:109], 12, v[108:109]
	v_lshl_add_u64 v[104:105], v[186:187], 0, v[104:105]
	v_lshl_add_u64 v[108:109], v[162:163], 0, v[108:109]
	v_lshlrev_b32_e32 v114, 16, v193
	v_and_b32_e32 v115, 0xffff0000, v193
	v_lshlrev_b32_e32 v116, 16, v194
	v_lshl_add_u64 v[164:165], v[104:105], 0, v[150:151]
	v_and_b32_e32 v117, 0xffff0000, v194
	v_lshlrev_b32_e32 v118, 16, v195
	v_and_b32_e32 v119, 0xffff0000, v195
	v_lshl_add_u64 v[120:121], v[108:109], 0, v[150:151]
	v_lshlrev_b32_e32 v122, 16, v196
	v_and_b32_e32 v123, 0xffff0000, v196
	v_lshlrev_b32_e32 v124, 16, v197
	v_and_b32_e32 v125, 0xffff0000, v197
	v_lshlrev_b32_e32 v126, 16, v198
	v_and_b32_e32 v127, 0xffff0000, v198
	v_lshlrev_b32_e32 v166, 16, v199
	v_and_b32_e32 v167, 0xffff0000, v199
	global_load_dwordx4 v[104:107], v[164:165], off
	global_load_dwordx4 v[108:111], v[120:121], off offset:2048
	v_pk_fma_f32 v[102:103], v[102:103], v[114:115], v[124:125]
	v_pk_fma_f32 v[100:101], v[100:101], v[112:113], v[122:123]
	v_pk_fma_f32 v[112:113], v[98:99], v[118:119], v[166:167]
	v_pk_fma_f32 v[98:99], v[96:97], v[116:117], v[126:127]
	v_cvt_pk_bf16_f32 v96, v100, v101
	v_cvt_pk_bf16_f32 v97, v102, v103
	v_cvt_pk_bf16_f32 v98, v98, v99
	v_cvt_pk_bf16_f32 v99, v112, v113
	v_add_u32_e32 v116, 48, v148
	global_store_dwordx4 v[158:159], v[96:99], off offset:256
	v_ashrrev_i32_e32 v117, 31, v116
	global_load_dwordx4 v[96:99], v[120:121], off offset:2304
	global_load_dwordx4 v[100:103], v[164:165], off offset:256
	v_lshlrev_b64 v[112:113], 12, v[116:117]
	v_lshl_add_u64 v[112:113], v[162:163], 0, v[112:113]
	v_lshl_add_u64 v[120:121], v[112:113], 0, v[150:151]
	v_lshlrev_b64 v[116:117], 11, v[116:117]
	global_load_dwordx4 v[112:115], v[120:121], off offset:2048
	v_lshl_add_u64 v[116:117], v[186:187], 0, v[116:117]
	v_lshl_add_u64 v[158:159], v[116:117], 0, v[150:151]
	global_load_dwordx4 v[116:119], v[158:159], off
	s_nop 0
	global_load_dwordx4 v[120:123], v[120:121], off offset:2304
	s_nop 0
	global_load_dwordx4 v[124:127], v[158:159], off offset:256
	s_waitcnt vmcnt(8)
	v_lshlrev_b32_e32 v166, 16, v104
	v_and_b32_e32 v167, 0xffff0000, v104
	v_lshlrev_b32_e32 v104, 16, v105
	v_and_b32_e32 v105, 0xffff0000, v105
	v_lshlrev_b32_e32 v168, 16, v106
	v_and_b32_e32 v169, 0xffff0000, v106
	v_lshlrev_b32_e32 v106, 16, v107
	s_waitcnt vmcnt(7)
	v_lshlrev_b32_e32 v170, 16, v108
	v_and_b32_e32 v171, 0xffff0000, v108
	v_lshlrev_b32_e32 v108, 16, v109
	v_and_b32_e32 v109, 0xffff0000, v109
	v_lshlrev_b32_e32 v172, 16, v110
	v_and_b32_e32 v173, 0xffff0000, v110
	v_lshlrev_b32_e32 v110, 16, v111
	v_and_b32_e32 v111, 0xffff0000, v111
	v_and_b32_e32 v107, 0xffff0000, v107
	v_pk_fma_f32 v[94:95], v[94:95], v[108:109], v[104:105]
	v_pk_fma_f32 v[92:93], v[92:93], v[170:171], v[166:167]
	v_pk_fma_f32 v[104:105], v[90:91], v[110:111], v[106:107]
	v_pk_fma_f32 v[90:91], v[88:89], v[172:173], v[168:169]
	v_cvt_pk_bf16_f32 v88, v92, v93
	v_cvt_pk_bf16_f32 v89, v94, v95
	v_cvt_pk_bf16_f32 v90, v90, v91
	v_cvt_pk_bf16_f32 v91, v104, v105
	global_store_dwordx4 v[164:165], v[88:91], off
	s_waitcnt vmcnt(6)
	v_lshlrev_b32_e32 v92, 16, v98
	v_and_b32_e32 v93, 0xffff0000, v98
	v_lshlrev_b32_e32 v88, 16, v96
	v_and_b32_e32 v89, 0xffff0000, v96
	v_lshlrev_b32_e32 v90, 16, v97
	v_and_b32_e32 v91, 0xffff0000, v97
	v_lshlrev_b32_e32 v94, 16, v99
	v_and_b32_e32 v95, 0xffff0000, v99
	s_waitcnt vmcnt(5)
	v_lshlrev_b32_e32 v96, 16, v100
	v_and_b32_e32 v97, 0xffff0000, v100
	v_lshlrev_b32_e32 v98, 16, v101
	v_and_b32_e32 v99, 0xffff0000, v101
	v_lshlrev_b32_e32 v100, 16, v102
	v_and_b32_e32 v101, 0xffff0000, v102
	v_lshlrev_b32_e32 v102, 16, v103
	v_and_b32_e32 v103, 0xffff0000, v103
	v_pk_fma_f32 v[86:87], v[86:87], v[90:91], v[98:99]
	v_pk_fma_f32 v[84:85], v[84:85], v[88:89], v[96:97]
	v_pk_fma_f32 v[88:89], v[82:83], v[94:95], v[102:103]
	v_pk_fma_f32 v[82:83], v[80:81], v[92:93], v[100:101]
	v_cvt_pk_bf16_f32 v80, v84, v85
	v_cvt_pk_bf16_f32 v81, v86, v87
	v_cvt_pk_bf16_f32 v82, v82, v83
	v_cvt_pk_bf16_f32 v83, v88, v89
	global_store_dwordx4 v[164:165], v[80:83], off offset:256
	s_waitcnt vmcnt(4)
	v_lshlrev_b32_e32 v88, 16, v116
	v_and_b32_e32 v89, 0xffff0000, v116
	v_lshlrev_b32_e32 v80, 16, v112
	v_and_b32_e32 v81, 0xffff0000, v112
	v_lshlrev_b32_e32 v82, 16, v113
	v_and_b32_e32 v83, 0xffff0000, v113
	v_lshlrev_b32_e32 v84, 16, v114
	v_and_b32_e32 v85, 0xffff0000, v114
	v_lshlrev_b32_e32 v86, 16, v115
	v_and_b32_e32 v87, 0xffff0000, v115
	v_lshlrev_b32_e32 v90, 16, v117
	v_and_b32_e32 v91, 0xffff0000, v117
	v_lshlrev_b32_e32 v92, 16, v118
	v_and_b32_e32 v93, 0xffff0000, v118
	v_lshlrev_b32_e32 v94, 16, v119
	v_and_b32_e32 v95, 0xffff0000, v119
	v_pk_fma_f32 v[76:77], v[76:77], v[80:81], v[88:89]
	v_pk_fma_f32 v[78:79], v[78:79], v[82:83], v[90:91]
	v_pk_fma_f32 v[80:81], v[74:75], v[86:87], v[94:95]
	v_pk_fma_f32 v[74:75], v[72:73], v[84:85], v[92:93]
	v_cvt_pk_bf16_f32 v72, v76, v77
	v_add_u32_e32 v76, 0x80, v148
	v_cvt_pk_bf16_f32 v73, v78, v79
	v_cvt_pk_bf16_f32 v74, v74, v75
	v_cvt_pk_bf16_f32 v75, v80, v81
	v_ashrrev_i32_e32 v77, 31, v76
	global_store_dwordx4 v[158:159], v[72:75], off
	s_waitcnt vmcnt(4)
	v_lshlrev_b32_e32 v80, 16, v120
	v_and_b32_e32 v81, 0xffff0000, v120
	v_lshlrev_b64 v[72:73], 12, v[76:77]
	v_lshlrev_b64 v[76:77], 11, v[76:77]
	v_lshl_add_u64 v[72:73], v[162:163], 0, v[72:73]
	v_lshl_add_u64 v[76:77], v[186:187], 0, v[76:77]
	v_lshlrev_b32_e32 v82, 16, v121
	v_and_b32_e32 v83, 0xffff0000, v121
	v_lshlrev_b32_e32 v84, 16, v122
	v_lshl_add_u64 v[86:87], v[72:73], 0, v[150:151]
	v_and_b32_e32 v85, 0xffff0000, v122
	v_lshlrev_b32_e32 v88, 16, v123
	v_and_b32_e32 v89, 0xffff0000, v123
	s_waitcnt vmcnt(3)
	v_lshlrev_b32_e32 v90, 16, v124
	v_lshl_add_u64 v[96:97], v[76:77], 0, v[150:151]
	v_and_b32_e32 v91, 0xffff0000, v124
	v_lshlrev_b32_e32 v92, 16, v125
	v_and_b32_e32 v93, 0xffff0000, v125
	v_lshlrev_b32_e32 v94, 16, v126
	v_and_b32_e32 v95, 0xffff0000, v126
	v_lshlrev_b32_e32 v98, 16, v127
	v_and_b32_e32 v99, 0xffff0000, v127
	global_load_dwordx4 v[72:75], v[86:87], off offset:2048
	global_load_dwordx4 v[76:79], v[96:97], off
	v_pk_fma_f32 v[70:71], v[70:71], v[82:83], v[92:93]
	v_pk_fma_f32 v[68:69], v[68:69], v[80:81], v[90:91]
	v_pk_fma_f32 v[80:81], v[66:67], v[88:89], v[98:99]
	v_pk_fma_f32 v[66:67], v[64:65], v[84:85], v[94:95]
	v_cvt_pk_bf16_f32 v64, v68, v69
	v_cvt_pk_bf16_f32 v65, v70, v71
	v_cvt_pk_bf16_f32 v66, v66, v67
	v_cvt_pk_bf16_f32 v67, v80, v81
	v_add_u32_e32 v84, 0x90, v148
	global_store_dwordx4 v[158:159], v[64:67], off offset:256
	s_bfe_u32 s99, s2, 0x10003
	s_sub_i32 s99, 2, s99
	s_cmp_eq_u32 s42, s99
	s_cbranch_scc0 .Lm1_epi_full
	s_cmp_eq_u32 s48, 0x100
	s_cbranch_scc1 .Lm1_epi_end
